# static s_setprio 1 for waves 4-7 (younger half) re-applied at each phase latch; GEMM per-segment flips untouched
# baseline (speedup 1.0000x reference)
.LBB0_18:
	v_readlane_b32 s98, v251, 7
	s_nop 3
	s_cmp_ge_u32 s98, 0x100
	s_cbranch_scc0 .Lprio_keep
	s_setprio 1
